# NA work queue hands out groups of 8 units per workgroup (4 column blocks x 2 adjacent rows of one head) so overlapping K/V windows hit in L1; cuts L2 traffic of the neighbourhood-attention phase
# speedup vs baseline: 1.0160x; 1.0084x over previous
; __device__ __forceinline__ void na_phase(const Params& p, LAS unsigned char* lds, unsigned* ctr, int wv) {
;     ...
;     for (;;) {
;         int id = 0;
;         if (lane == 0) id = (int)atomicAdd(ctr, 1u);
;         id = __builtin_amdgcn_readfirstlane(id);
;         if (id >= NA_UNITS) break;
.LBB0_641:
	s_barrier
	s_cmp_lg_u32 s90, 0
	s_cbranch_scc1 .Lna_bcast
	v_mov_b32_e32 v0, 0
	s_and_saveexec_b64 s[0:1], s[2:3]
	s_cbranch_execz .LBB0_645
	s_mov_b64 s[10:11], exec
	v_mbcnt_lo_u32_b32 v0, s10, 0
	v_mbcnt_hi_u32_b32 v0, s11, v0
	v_cmp_eq_u32_e32 vcc, 0, v0
	s_and_saveexec_b64 s[8:9], vcc
	s_cbranch_execz .LBB0_644
	s_bcnt1_i32_b64 s6, s[10:11]
	v_mov_b32_e32 v1, s6
	global_atomic_add v1, v83, v1, s[94:95] sc0

; __device__ __forceinline__ void na_unit(const Params& p, int id, int lane, const LAS float* rbt) {
;     ...
;     if (id < NB * 256 * 4 * 8) { h = id & 7; j = (id >> 3) & 3; r = (id >> 5) & 255; b = id >> 13;
;         r0 = r - 4; r0 = r0 < 0 ? 0 : (r0 > 248 ? 248 : r0); cs = 16 * j - 8; cs = cs < 0 ? 0 : (cs > 32 ? 32 : cs);
;         qtok = b * T + 16 + r * 64 + 16 * j; meta = false; }
;     else { const int m = id - NB * 256 * 4 * 8; h = m & 7; b = m >> 3; qtok = b * T; meta = true; }
; __device__ __forceinline__ void na_phase(const Params& p, LAS unsigned char* lds, unsigned* ctr, int wv) {
;     ...
;     for (;;) {
;         int id = 0;
;         if (lane == 0) id = (int)atomicAdd(ctr, 1u);
;         id = __builtin_amdgcn_readfirstlane(id);
;         if (id >= NA_UNITS) break;
;         na_unit(p, id, lane, rbt);
.LBB0_645:
	s_or_b64 exec, exec, s[0:1]
	v_readfirstlane_b32 s6, v0
	v_mov_b32_e32 v1, 0x8000
	v_mov_b32_e32 v0, s6
	ds_write_b32 v1, v0
	s_waitcnt lgkmcnt(0)
.Lna_bcast:
	s_barrier
	v_mov_b32_e32 v0, 0x8000
	ds_read_b32 v0, v0
	s_waitcnt lgkmcnt(0)
	s_nop 0
	v_readfirstlane_b32 s6, v0
	s_cmpk_gt_i32 s6, 0x801
	s_mov_b64 s[0:1], -1
	s_cbranch_scc1 .LBB0_640
	s_lshr_b32 s98, s90, 6
	s_cmpk_gt_i32 s6, 0x7ff
	s_cbranch_scc1 .Lna_meta
	s_lshr_b32 s8, s6, 10
	s_lshl_b32 s8, s8, 13
	s_bfe_u32 s9, s6, 0x30007
	s_or_b32 s8, s8, s9
	s_and_b32 s9, s6, 0x7f
	s_lshl_b32 s9, s9, 1
	s_lshr_b32 s10, s98, 2
	s_add_i32 s9, s9, s10
	s_lshl_b32 s9, s9, 5
	s_or_b32 s8, s8, s9
	s_and_b32 s9, s98, 3
	s_lshl_b32 s9, s9, 3
	s_or_b32 s6, s8, s9
	s_branch .Lna_go
.Lna_meta:
	s_lshl_b32 s6, s6, 3
	s_add_i32 s6, s6, s98
.Lna_go:
	s_cmpk_lt_i32 s6, 0x4000
	s_cselect_b64 s[0:1], -1, 0
	s_cmpk_gt_i32 s6, 0x3fff
	s_cbranch_scc1 .LBB0_648
	s_ashr_i32 s14, s6, 13
	s_lshl_b32 s8, s6, 1
	s_bfe_u32 s12, s6, 0x80005
	s_and_b32 s13, s8, 48
	s_mul_i32 s8, s14, 0x4010
	v_med3_u32 v0, s12, 4, v111
	s_add_i32 s8, s8, s13
	s_lshl_b32 s9, s12, 6
	v_add_u32_e32 v64, -4, v0
	v_med3_u32 v0, s13, 8, 40
	s_add_i32 s8, s8, s9
	v_add_u32_e32 v65, -8, v0
	s_add_i32 s10, s8, 16
	s_cbranch_execz .LBB0_649
	s_branch .LBB0_650
